# odd quads enter the per-quad stage chain ~10us late (3 x s_sleep 127 before S2) so the two halves' epilogue memory bursts do not coincide
# speedup vs baseline: 1.0075x; 1.0075x over previous
.LBB0_785:
	s_or_b64 exec, exec, s[2:3]
	s_cmp_lt_i32 s88, 5
	s_cselect_b64 s[0:1], -1, 0
	s_cmp_gt_i32 s89, 4
	s_cselect_b64 s[2:3], -1, 0
	s_and_b64 s[0:1], s[0:1], s[2:3]
	s_andn2_b64 vcc, exec, s[0:1]
	s_cbranch_vccnz .LBB0_869
	s_bitcmp1_b32 s86, 2
	s_cbranch_scc0 .Lqstag_skip
	s_sleep 127
	s_sleep 127
	s_sleep 127
.Lqstag_skip:
	s_and_saveexec_b64 s[6:7], s[80:81]
	s_cbranch_execz .LBB0_815
	s_lshl_b32 s8, s33, 4
	s_ashr_i32 s9, s8, 31
	s_lshl_b64 s[0:1], s[8:9], 2
	v_readlane_b32 s2, v246, 2
	v_readlane_b32 s3, v246, 3
	s_add_u32 s0, s2, s0
	s_addc_u32 s1, s3, s1
	v_mov_b32_e32 v1, 0x1000
	global_load_dword v1, v1, s[0:1] sc1
	buffer_inv sc1
	s_add_u32 s12, s0, 0x1000
	s_addc_u32 s13, s1, 0
	s_waitcnt vmcnt(0)
	v_cmp_lt_u32_e32 vcc, 3, v1
	s_cbranch_vccnz .LBB0_800
	v_readlane_b32 s0, v246, 2
	v_readlane_b32 s1, v246, 3
	s_add_u32 s10, s0, 0x4200
	s_addc_u32 s11, s1, 0
	s_mov_b32 s0, 1
	v_mov_b32_e32 v1, 0
	s_branch .LBB0_790
